# attention tile loop: second sub-tile's first K/Q score-operand reads issued inside the first sub-tile's map-1 PV MFMAs
# speedup vs baseline: 1.0075x; 1.0075x over previous
; #define LAS __attribute__((address_space(3)))
; __device__ __forceinline__ void dattn_unit(LAS unsigned char* lds, int b, int h, int qb, const bf16* Q, const bf16* K, const bf16* V, bf16* YB, float lam, const float* subg, float oml, int tid) {
;     ...
;                 const LAS bf16* kp = Ks + (32 * sub + ql) * 72 + hi * 8;
;                 bf16x8 ka = *(const LAS bf16x8*)kp, kb = *(const LAS bf16x8*)(kp + 64 * 72), qa = qsp[0], qb = qsp[4 * 64];
;     ...
;             for (int cb = 0; cb < 4; ++cb) { const LAS bf16* vp = Vt + (32 * cb + ql) * 72 + 32 * sub + 4 * hi;
;                 const v2u a0 = *(const LAS v2u*)(vp), a1 = *(const LAS v2u*)(vp + 8), a2 = *(const LAS v2u*)(vp + 16), a3 = *(const LAS v2u*)(vp + 24);
;                 const v4u f0 = {a0.x, a0.y, a1.x, a1.y}, f1 = {a2.x, a2.y, a3.x, a3.y};
;                 o[0][cb] = __builtin_amdgcn_mfma_f32_32x32x16_bf16(__builtin_bit_cast(bf16x8, f0), pA0, o[0][cb], 0, 0, 0);
;                 o[1][cb] = __builtin_amdgcn_mfma_f32_32x32x16_bf16(__builtin_bit_cast(bf16x8, f0), pA1, o[1][cb], 0, 0, 0);
;                 o[0][cb] = __builtin_amdgcn_mfma_f32_32x32x16_bf16(__builtin_bit_cast(bf16x8, f1), pB0, o[0][cb], 0, 0, 0);
;                 o[1][cb] = __builtin_amdgcn_mfma_f32_32x32x16_bf16(__builtin_bit_cast(bf16x8, f1), pB1, o[1][cb], 0, 0, 0); }
.LBB0_234:
	v_cvt_pk_bf16_f32 v152, v155, v129
	v_cvt_pk_bf16_f32 v153, v130, v131
	v_cvt_pk_bf16_f32 v154, v132, v156
	v_cvt_pk_bf16_f32 v155, v157, v158
	v_cvt_pk_bf16_f32 v130, v133, v134
	v_cvt_pk_bf16_f32 v131, v135, v136
	v_cvt_pk_bf16_f32 v132, v137, v138
	v_cvt_pk_bf16_f32 v133, v139, v140
	s_andn2_b64 vcc, exec, s[48:49]
	s_nop 0
	v_mfma_f32_32x32x16_bf16 v[64:79], v[228:231], v[152:155], v[64:79]
	ds_read_b128 v[138:141], v199 offset:4608
	v_mfma_f32_32x32x16_bf16 v[64:79], v[232:235], v[130:133], v[64:79]
	v_mfma_f32_32x32x16_bf16 v[32:47], v[236:239], v[152:155], v[32:47]
	v_mfma_f32_32x32x16_bf16 v[32:47], v[240:243], v[130:133], v[32:47]
	v_mfma_f32_32x32x16_bf16 v[96:111], v[220:223], v[152:155], v[96:111]
	ds_read_b128 v[218:221], v189
	ds_read_b128 v[222:225], v189 offset:4096
	v_mfma_f32_32x32x16_bf16 v[96:111], v[204:207], v[130:133], v[96:111]
	ds_read_b128 v[204:207], v199 offset:13824
	v_mfma_f32_32x32x16_bf16 v[0:15], v[212:215], v[152:155], v[0:15]
	s_nop 0
	v_mfma_f32_32x32x16_bf16 v[0:15], v[200:203], v[130:133], v[0:15]
	s_cbranch_vccnz .LBB0_236
	v_log_f32_e32 v129, v146
	s_nop 0
	v_max_f32_e32 v129, 0, v129
	v_exp_f32_e64 v130, -v129
	v_add_f32_e32 v190, v190, v129
	s_nop 1
	v_pk_mul_f32 v[126:127], v[130:131], v[126:127] op_sel_hi:[0,1]
	v_pk_mul_f32 v[124:125], v[130:131], v[124:125] op_sel_hi:[0,1]
	v_pk_mul_f32 v[122:123], v[130:131], v[122:123] op_sel_hi:[0,1]
	v_pk_mul_f32 v[120:121], v[130:131], v[120:121] op_sel_hi:[0,1]
	v_pk_mul_f32 v[118:119], v[130:131], v[118:119] op_sel_hi:[0,1]
	v_pk_mul_f32 v[116:117], v[130:131], v[116:117] op_sel_hi:[0,1]
	v_pk_mul_f32 v[114:115], v[130:131], v[114:115] op_sel_hi:[0,1]
	v_pk_mul_f32 v[112:113], v[130:131], v[112:113] op_sel_hi:[0,1]
	v_pk_mul_f32 v[94:95], v[130:131], v[94:95] op_sel_hi:[0,1]
	v_pk_mul_f32 v[92:93], v[130:131], v[92:93] op_sel_hi:[0,1]
	v_pk_mul_f32 v[90:91], v[130:131], v[90:91] op_sel_hi:[0,1]
	v_pk_mul_f32 v[88:89], v[130:131], v[88:89] op_sel_hi:[0,1]
	v_pk_mul_f32 v[86:87], v[130:131], v[86:87] op_sel_hi:[0,1]
	v_pk_mul_f32 v[84:85], v[130:131], v[84:85] op_sel_hi:[0,1]
	v_pk_mul_f32 v[82:83], v[130:131], v[82:83] op_sel_hi:[0,1]
	v_pk_mul_f32 v[80:81], v[130:131], v[80:81] op_sel_hi:[0,1]
	v_pk_mul_f32 v[62:63], v[130:131], v[62:63] op_sel_hi:[0,1]
	v_pk_mul_f32 v[60:61], v[130:131], v[60:61] op_sel_hi:[0,1]
	v_pk_mul_f32 v[58:59], v[130:131], v[58:59] op_sel_hi:[0,1]
	v_pk_mul_f32 v[56:57], v[130:131], v[56:57] op_sel_hi:[0,1]
	v_pk_mul_f32 v[54:55], v[130:131], v[54:55] op_sel_hi:[0,1]
	v_pk_mul_f32 v[52:53], v[130:131], v[52:53] op_sel_hi:[0,1]
	v_pk_mul_f32 v[50:51], v[130:131], v[50:51] op_sel_hi:[0,1]
	v_pk_mul_f32 v[48:49], v[130:131], v[48:49] op_sel_hi:[0,1]
	v_pk_mul_f32 v[30:31], v[130:131], v[30:31] op_sel_hi:[0,1]
	v_pk_mul_f32 v[28:29], v[130:131], v[28:29] op_sel_hi:[0,1]
	v_pk_mul_f32 v[26:27], v[130:131], v[26:27] op_sel_hi:[0,1]
	v_pk_mul_f32 v[24:25], v[130:131], v[24:25] op_sel_hi:[0,1]
	v_pk_mul_f32 v[22:23], v[130:131], v[22:23] op_sel_hi:[0,1]
	v_pk_mul_f32 v[20:21], v[130:131], v[20:21] op_sel_hi:[0,1]
	v_pk_mul_f32 v[18:19], v[130:131], v[18:19] op_sel_hi:[0,1]
	v_pk_mul_f32 v[16:17], v[130:131], v[16:17] op_sel_hi:[0,1]
	v_mul_f32_e32 v179, v179, v130

; #define LAS __attribute__((address_space(3)))
; __device__ __forceinline__ void dattn_unit(LAS unsigned char* lds, int b, int h, int qb, const bf16* Q, const bf16* K, const bf16* V, bf16* YB, float lam, const float* subg, float oml, int tid) {
;     ...
;             if (kvbase + 32 * sub > qmax) continue;
;             const bool need_bm = kvbase + 32 * sub + 31 + 113 > qmin;
;             LAS bf16x8* qsp = qs; asm volatile("" : "+v"(qsp));
;             f32x16 s0, s1;
; #pragma unroll
;             for (int r = 0; r < 16; ++r) { s0[r] = -mref[0]; s1[r] = -mref[1]; }
;             {
;                 const LAS bf16* kp = Ks + (32 * sub + ql) * 72 + hi * 8;
;                 bf16x8 ka = *(const LAS bf16x8*)kp, kb = *(const LAS bf16x8*)(kp + 64 * 72), qa = qsp[0], qb = qsp[4 * 64];
;                 __builtin_amdgcn_sched_group_barrier(0x100, 4, 0);
; #pragma unroll
;                 for (int ks = 0; ks < 4; ++ks) { bf16x8 ka2 = ka, kb2 = kb, qa2 = qa, qb2 = qb;
;                     if (ks < 3) { ka2 = *(const LAS bf16x8*)(kp + (ks + 1) * 16); kb2 = *(const LAS bf16x8*)(kp + 64 * 72 + (ks + 1) * 16); qa2 = qsp[(ks + 1) * 64]; qb2 = qsp[(4 + ks + 1) * 64];
;                         __builtin_amdgcn_sched_group_barrier(0x100, 4, 0); }
;                     s0 = __builtin_amdgcn_mfma_f32_32x32x16_bf16(ka, qa, s0, 0, 0, 0);
;                     s1 = __builtin_amdgcn_mfma_f32_32x32x16_bf16(kb, qb, s1, 0, 0, 0);
;                     __builtin_amdgcn_sched_group_barrier(0x008, 2, 0);
;                     ka = ka2; kb = kb2; qa = qa2; qb = qb2; }
;             }
.LBB0_238:
	s_add_i32 s18, s58, 0xffffff70
	s_cmp_gt_i32 s18, s35
	s_cbranch_scc1 .LBB0_226
	v_xor_b32_e32 v144, 0x80000000, v190
	v_xor_b32_e32 v128, 0x80000000, v191
	v_mov_b32_e32 v145, v144
	v_mov_b64_e32 v[146:147], v[144:145]
	v_mov_b64_e32 v[148:149], v[144:145]
	v_mov_b64_e32 v[150:151], v[144:145]
	v_mov_b64_e32 v[152:153], v[144:145]
	v_mov_b64_e32 v[154:155], v[144:145]
	v_mov_b64_e32 v[156:157], v[144:145]
	v_mov_b64_e32 v[158:159], v[144:145]
	v_mov_b32_e32 v129, v128
	v_mov_b64_e32 v[130:131], v[128:129]
	v_mov_b64_e32 v[132:133], v[128:129]
	v_mov_b64_e32 v[134:135], v[128:129]
	v_mov_b64_e32 v[136:137], v[128:129]
	ds_read_b128 v[226:229], v199 offset:4640
	ds_read_b128 v[230:233], v199 offset:13856
	ds_read_b128 v[234:237], v189 offset:1024
	ds_read_b128 v[238:241], v189 offset:5120
	s_waitcnt lgkmcnt(5)
	v_mfma_f32_32x32x16_bf16 v[144:159], v[138:141], v[218:221], v[144:159]
	v_mov_b64_e32 v[142:143], v[128:129]
	v_mov_b64_e32 v[138:139], v[128:129]
	v_mov_b64_e32 v[140:141], v[128:129]
	s_cmp_le_i32 s58, s31
	s_waitcnt lgkmcnt(4)
	v_mfma_f32_32x32x16_bf16 v[128:143], v[204:207], v[222:225], v[128:143]
	ds_read_b128 v[204:207], v199 offset:4672
	ds_read_b128 v[218:221], v199 offset:13888
	ds_read_b128 v[222:225], v189 offset:2048
	ds_read_b128 v[212:215], v189 offset:6144
	s_waitcnt lgkmcnt(5)
	v_mfma_f32_32x32x16_bf16 v[144:159], v[226:229], v[234:237], v[144:159]
	s_waitcnt lgkmcnt(4)
	v_mfma_f32_32x32x16_bf16 v[128:143], v[230:233], v[238:241], v[128:143]
	ds_read_b128 v[226:229], v199 offset:4704
	ds_read_b128 v[230:233], v199 offset:13920
	ds_read_b128 v[234:237], v189 offset:3072
	ds_read_b128 v[238:241], v189 offset:7168
	s_waitcnt lgkmcnt(5)
	v_mfma_f32_32x32x16_bf16 v[144:159], v[204:207], v[222:225], v[144:159]
	s_cbranch_scc0 .Lqk_diag1
	s_waitcnt lgkmcnt(1)
	v_mfma_f32_32x32x16_bf16 v[144:159], v[226:229], v[234:237], v[144:159]
	v_add3_u32 v243, s38, v193, v192
	ds_read_b128 v[222:225], v243 offset:23104
	ds_read_b128 v[226:229], v243 offset:23136
	v_mfma_f32_32x32x16_bf16 v[128:143], v[218:221], v[212:215], v[128:143]
	s_waitcnt lgkmcnt(2)
	v_mfma_f32_32x32x16_bf16 v[128:143], v[230:233], v[238:241], v[128:143]
	ds_read_b128 v[230:233], v243 offset:27712
	ds_read_b128 v[234:237], v243 offset:27744
	ds_read_b128 v[238:241], v243 offset:32320
	ds_read_b128 v[212:215], v243 offset:18496
	ds_read_b128 v[200:203], v243 offset:18528
	s_nop 1
